# QKV epilogue: the 16 serialised LDS partial-sum reads pipelined 8 deep (v218-249) instead of one lgkmcnt(0) round trip each
# speedup vs baseline: 1.0021x; 1.0003x over previous
;     __device__ __forceinline__ void operator()(const f32x4 (&acc)[2][2][4][2], const Unit& u, int wr, int wc, int fr, int fq) const {
;     ...
;             if (kind != 2) {
; #pragma unroll
;                 for (int ai = 0; ai < 2; ++ai)
; #pragma unroll
;                     for (int bj = 0; bj < 2; ++bj)
; #pragma unroll
;                         for (int m = 0; m < 4; ++m) { const f32x4 a = acc[ai][bj][m][0], b = acc[ai][bj][m][1];
;                             float q = a[0] * a[0]; q = __builtin_fmaf(a[1], a[1], q); q = __builtin_fmaf(a[2], a[2], q); q = __builtin_fmaf(a[3], a[3], q);
;                             q = __builtin_fmaf(b[0], b[0], q); q = __builtin_fmaf(b[1], b[1], q); q = __builtin_fmaf(b[2], b[2], q); q = __builtin_fmaf(b[3], b[3], q);
;                             q = fq_sum(q);
;                             if (fq == 0) red[((ai * HALF + wr * 64 + m * 16 + fr) * 2 + bj) * 4 + wc] = q; }
.LBB0_412:
	s_and_b32 s0, s52, -8
	s_cmp_lg_u32 s0, 16
	s_mov_b64 s[0:1], -1
	s_cbranch_scc0 .LBB0_446
	v_mul_f32_e32 v2, v128, v128
	v_fmac_f32_e32 v2, v129, v129
	v_fmac_f32_e32 v2, v130, v130
	v_fmac_f32_e32 v2, v131, v131
	v_fmac_f32_e32 v2, v124, v124
	v_fmac_f32_e32 v2, v125, v125
	v_fmac_f32_e32 v2, v126, v126
	v_fmac_f32_e32 v2, v127, v127
	v_mov_b32_e32 v133, v2
	s_nop 1
	v_permlane16_swap_b32_e32 v2, v133
	v_add_f32_e32 v133, v2, v133
	v_mov_b32_e32 v135, v133
	s_nop 1
	v_permlane32_swap_b32_e32 v133, v135
	v_add_u32_e32 v2, s46, v187
	s_and_saveexec_b64 s[0:1], s[38:39]
	v_add_f32_e32 v133, v133, v135
	ds_write_b32 v2, v133
	s_or_b64 exec, exec, s[0:1]
	v_mul_f32_e32 v133, v112, v112
	v_fmac_f32_e32 v133, v113, v113
	v_fmac_f32_e32 v133, v114, v114
	v_fmac_f32_e32 v133, v115, v115
	v_fmac_f32_e32 v133, v108, v108
	v_fmac_f32_e32 v133, v109, v109
	v_fmac_f32_e32 v133, v110, v110
	v_fmac_f32_e32 v133, v111, v111
	v_mov_b32_e32 v135, v133
	s_nop 1
	v_permlane16_swap_b32_e32 v133, v135
	v_add_f32_e32 v133, v133, v135
	v_mov_b32_e32 v135, v133
	s_nop 1
	v_permlane32_swap_b32_e32 v133, v135
	s_and_saveexec_b64 s[0:1], s[38:39]
	v_add_f32_e32 v133, v133, v135
	ds_write_b32 v2, v133 offset:512
	s_or_b64 exec, exec, s[0:1]
	v_mul_f32_e32 v133, v96, v96
	v_fmac_f32_e32 v133, v97, v97
	v_fmac_f32_e32 v133, v98, v98
	v_fmac_f32_e32 v133, v99, v99
	v_fmac_f32_e32 v133, v92, v92
	v_fmac_f32_e32 v133, v93, v93
	v_fmac_f32_e32 v133, v94, v94
	v_fmac_f32_e32 v133, v95, v95
	v_mov_b32_e32 v135, v133
	s_nop 1
	v_permlane16_swap_b32_e32 v133, v135
	v_add_f32_e32 v133, v133, v135
	v_mov_b32_e32 v135, v133
	s_nop 1
	v_permlane32_swap_b32_e32 v133, v135
	s_and_saveexec_b64 s[0:1], s[38:39]
	v_add_f32_e32 v133, v133, v135
	ds_write_b32 v2, v133 offset:1024
	s_or_b64 exec, exec, s[0:1]
	v_mul_f32_e32 v133, v80, v80
	v_fmac_f32_e32 v133, v81, v81
	v_fmac_f32_e32 v133, v82, v82
	v_fmac_f32_e32 v133, v83, v83
	v_fmac_f32_e32 v133, v76, v76
	v_fmac_f32_e32 v133, v77, v77
	v_fmac_f32_e32 v133, v78, v78
	v_fmac_f32_e32 v133, v79, v79
	v_mov_b32_e32 v135, v133
	s_nop 1
	v_permlane16_swap_b32_e32 v133, v135
	v_add_f32_e32 v133, v133, v135
	v_mov_b32_e32 v135, v133
	s_nop 1
	v_permlane32_swap_b32_e32 v133, v135
	s_and_saveexec_b64 s[0:1], s[38:39]
	v_add_f32_e32 v133, v133, v135
	ds_write_b32 v2, v133 offset:1536
	s_or_b64 exec, exec, s[0:1]
	v_mul_f32_e32 v133, v120, v120
	v_fmac_f32_e32 v133, v121, v121
	v_fmac_f32_e32 v133, v122, v122
	v_fmac_f32_e32 v133, v123, v123
	v_fmac_f32_e32 v133, v116, v116
	v_fmac_f32_e32 v133, v117, v117
	v_fmac_f32_e32 v133, v118, v118
	v_fmac_f32_e32 v133, v119, v119
	v_mov_b32_e32 v135, v133
	s_nop 1
	v_permlane16_swap_b32_e32 v133, v135
	v_add_f32_e32 v135, v133, v135
	v_mov_b32_e32 v137, v135
	s_nop 1
	v_permlane32_swap_b32_e32 v135, v137
	v_add_u32_e32 v133, s47, v187
	s_and_saveexec_b64 s[0:1], s[38:39]
	v_add_f32_e32 v135, v135, v137
	ds_write_b32 v133, v135
	s_or_b64 exec, exec, s[0:1]
	v_mul_f32_e32 v135, v104, v104
	v_fmac_f32_e32 v135, v105, v105
	v_fmac_f32_e32 v135, v106, v106
	v_fmac_f32_e32 v135, v107, v107
	v_fmac_f32_e32 v135, v100, v100
	v_fmac_f32_e32 v135, v101, v101
	v_fmac_f32_e32 v135, v102, v102
	v_fmac_f32_e32 v135, v103, v103
	v_mov_b32_e32 v137, v135
	s_nop 1
	v_permlane16_swap_b32_e32 v135, v137
	v_add_f32_e32 v135, v135, v137
	v_mov_b32_e32 v137, v135
	s_nop 1
	v_permlane32_swap_b32_e32 v135, v137
	s_and_saveexec_b64 s[0:1], s[38:39]
	v_add_f32_e32 v135, v135, v137
	ds_write_b32 v133, v135 offset:512
	s_or_b64 exec, exec, s[0:1]
	v_mul_f32_e32 v135, v88, v88
	v_fmac_f32_e32 v135, v89, v89
	v_fmac_f32_e32 v135, v90, v90
	v_fmac_f32_e32 v135, v91, v91
	v_fmac_f32_e32 v135, v84, v84
	v_fmac_f32_e32 v135, v85, v85
	v_fmac_f32_e32 v135, v86, v86
	v_fmac_f32_e32 v135, v87, v87
	v_mov_b32_e32 v137, v135
	s_nop 1
	v_permlane16_swap_b32_e32 v135, v137
	v_add_f32_e32 v135, v135, v137
	v_mov_b32_e32 v137, v135
	s_nop 1
	v_permlane32_swap_b32_e32 v135, v137
	s_and_saveexec_b64 s[0:1], s[38:39]
	v_add_f32_e32 v135, v135, v137
	ds_write_b32 v133, v135 offset:1024
	s_or_b64 exec, exec, s[0:1]
	v_mul_f32_e32 v135, v72, v72
	v_fmac_f32_e32 v135, v73, v73
	v_fmac_f32_e32 v135, v74, v74
	v_fmac_f32_e32 v135, v75, v75
	v_fmac_f32_e32 v135, v68, v68
	v_fmac_f32_e32 v135, v69, v69
	v_fmac_f32_e32 v135, v70, v70
	v_fmac_f32_e32 v135, v71, v71
	v_mov_b32_e32 v137, v135
	s_nop 1
	v_permlane16_swap_b32_e32 v135, v137
	v_add_f32_e32 v135, v135, v137
	v_mov_b32_e32 v137, v135
	s_nop 1
	v_permlane32_swap_b32_e32 v135, v137
	s_and_saveexec_b64 s[0:1], s[38:39]
	v_add_f32_e32 v135, v135, v137
	ds_write_b32 v133, v135 offset:1536
	s_or_b64 exec, exec, s[0:1]
	v_mul_f32_e32 v135, v64, v64
	v_fmac_f32_e32 v135, v65, v65
	v_fmac_f32_e32 v135, v66, v66
	v_fmac_f32_e32 v135, v67, v67
	v_fmac_f32_e32 v135, v60, v60
	v_fmac_f32_e32 v135, v61, v61
	v_fmac_f32_e32 v135, v62, v62
	v_fmac_f32_e32 v135, v63, v63
	v_mov_b32_e32 v137, v135
	s_nop 1
	v_permlane16_swap_b32_e32 v135, v137
	v_add_f32_e32 v135, v135, v137
	v_mov_b32_e32 v137, v135
	s_nop 1
	v_permlane32_swap_b32_e32 v135, v137
	s_and_saveexec_b64 s[0:1], s[38:39]
	v_add_f32_e32 v135, v135, v137
	ds_write_b32 v2, v135 offset:4096
	s_or_b64 exec, exec, s[0:1]
	v_mul_f32_e32 v135, v48, v48
	v_fmac_f32_e32 v135, v49, v49
	v_fmac_f32_e32 v135, v50, v50
	v_fmac_f32_e32 v135, v51, v51
	v_fmac_f32_e32 v135, v44, v44
	v_fmac_f32_e32 v135, v45, v45
	v_fmac_f32_e32 v135, v46, v46
	v_fmac_f32_e32 v135, v47, v47
	v_mov_b32_e32 v137, v135
	s_nop 1
	v_permlane16_swap_b32_e32 v135, v137
	v_add_f32_e32 v135, v135, v137
	v_mov_b32_e32 v137, v135
	s_nop 1
	v_permlane32_swap_b32_e32 v135, v137
; #define PG8_LAS __attribute__((address_space(3)))
;     __device__ __forceinline__ void operator()(const f32x4 (&acc)[2][2][4][2], const Unit& u, int wr, int wc, int fr, int fq) const {
;     ...
;                 asm volatile("s_waitcnt lgkmcnt(0)" ::: "memory");
;                 __builtin_amdgcn_s_barrier();
; #pragma unroll
;                 for (int ai = 0; ai < 2; ++ai)
; #pragma unroll
;                     for (int bj = 0; bj < 2; ++bj)
; #pragma unroll
;                         for (int m = 0; m < 4; ++m) { const f32x4 r4 = *(const PG8_LAS f32x4*)(red + ((ai * HALF + wr * 64 + m * 16 + fr) * 2 + bj) * 4);
;                             sc[ai][bj][m] = __builtin_amdgcn_rsqf(((r4[0] + r4[1]) + (r4[2] + r4[3])) * (1.f / 128.f) + 1e-6f * var[ai][m]); }
	s_and_saveexec_b64 s[0:1], s[38:39]
	v_add_f32_e32 v135, v135, v137
	ds_write_b32 v2, v135 offset:4608
	s_or_b64 exec, exec, s[0:1]
	v_mul_f32_e32 v135, v32, v32
	v_fmac_f32_e32 v135, v33, v33
	v_fmac_f32_e32 v135, v34, v34
	v_fmac_f32_e32 v135, v35, v35
	v_fmac_f32_e32 v135, v28, v28
	v_fmac_f32_e32 v135, v29, v29
	v_fmac_f32_e32 v135, v30, v30
	v_fmac_f32_e32 v135, v31, v31
	v_mov_b32_e32 v137, v135
	s_nop 1
	v_permlane16_swap_b32_e32 v135, v137
	v_add_f32_e32 v135, v135, v137
	v_mov_b32_e32 v137, v135
	s_nop 1
	v_permlane32_swap_b32_e32 v135, v137
	s_and_saveexec_b64 s[0:1], s[38:39]
	v_add_f32_e32 v135, v135, v137
	ds_write_b32 v2, v135 offset:5120
	s_or_b64 exec, exec, s[0:1]
	v_mul_f32_e32 v135, v16, v16
	v_fmac_f32_e32 v135, v17, v17
	v_fmac_f32_e32 v135, v18, v18
	v_fmac_f32_e32 v135, v19, v19
	v_fmac_f32_e32 v135, v12, v12
	v_fmac_f32_e32 v135, v13, v13
	v_fmac_f32_e32 v135, v14, v14
	v_fmac_f32_e32 v135, v15, v15
	v_mov_b32_e32 v137, v135
	s_nop 1
	v_permlane16_swap_b32_e32 v135, v137
	v_add_f32_e32 v135, v135, v137
	v_mov_b32_e32 v137, v135
	s_nop 1
	v_permlane32_swap_b32_e32 v135, v137
	s_and_saveexec_b64 s[0:1], s[38:39]
	v_add_f32_e32 v135, v135, v137
	ds_write_b32 v2, v135 offset:5632
	s_or_b64 exec, exec, s[0:1]
	v_mul_f32_e32 v2, v56, v56
	v_fmac_f32_e32 v2, v57, v57
	v_fmac_f32_e32 v2, v58, v58
	v_fmac_f32_e32 v2, v59, v59
	v_fmac_f32_e32 v2, v52, v52
	v_fmac_f32_e32 v2, v53, v53
	v_fmac_f32_e32 v2, v54, v54
	v_fmac_f32_e32 v2, v55, v55
	v_mov_b32_e32 v135, v2
	s_nop 1
	v_permlane16_swap_b32_e32 v2, v135
	v_add_f32_e32 v2, v2, v135
	v_mov_b32_e32 v135, v2
	s_nop 1
	v_permlane32_swap_b32_e32 v2, v135
	s_and_saveexec_b64 s[0:1], s[38:39]
	v_add_f32_e32 v2, v2, v135
	ds_write_b32 v133, v2 offset:4096
	s_or_b64 exec, exec, s[0:1]
	v_mul_f32_e32 v2, v40, v40
	v_fmac_f32_e32 v2, v41, v41
	v_fmac_f32_e32 v2, v42, v42
	v_fmac_f32_e32 v2, v43, v43
	v_fmac_f32_e32 v2, v36, v36
	v_fmac_f32_e32 v2, v37, v37
	v_fmac_f32_e32 v2, v38, v38
	v_fmac_f32_e32 v2, v39, v39
	v_mov_b32_e32 v135, v2
	s_nop 1
	v_permlane16_swap_b32_e32 v2, v135
	v_add_f32_e32 v2, v2, v135
	v_mov_b32_e32 v135, v2
	s_nop 1
	v_permlane32_swap_b32_e32 v2, v135
	s_and_saveexec_b64 s[0:1], s[38:39]
	v_add_f32_e32 v2, v2, v135
	ds_write_b32 v133, v2 offset:4608
	s_or_b64 exec, exec, s[0:1]
	v_mul_f32_e32 v2, v24, v24
	v_fmac_f32_e32 v2, v25, v25
	v_fmac_f32_e32 v2, v26, v26
	v_fmac_f32_e32 v2, v27, v27
	v_fmac_f32_e32 v2, v20, v20
	v_fmac_f32_e32 v2, v21, v21
	v_fmac_f32_e32 v2, v22, v22
	v_fmac_f32_e32 v2, v23, v23
	v_mov_b32_e32 v135, v2
	s_nop 1
	v_permlane16_swap_b32_e32 v2, v135
	v_add_f32_e32 v2, v2, v135
	v_mov_b32_e32 v135, v2
	s_nop 1
	v_permlane32_swap_b32_e32 v2, v135
	s_and_saveexec_b64 s[0:1], s[38:39]
	v_add_f32_e32 v2, v2, v135
	ds_write_b32 v133, v2 offset:5120
	s_or_b64 exec, exec, s[0:1]
	v_mul_f32_e32 v2, v8, v8
	v_fmac_f32_e32 v2, v9, v9
	v_fmac_f32_e32 v2, v10, v10
	v_fmac_f32_e32 v2, v11, v11
	v_fmac_f32_e32 v2, v4, v4
	v_fmac_f32_e32 v2, v5, v5
	v_fmac_f32_e32 v2, v6, v6
	v_fmac_f32_e32 v2, v7, v7
	v_mov_b32_e32 v135, v2
	s_nop 1
	v_permlane16_swap_b32_e32 v2, v135
	v_add_f32_e32 v2, v2, v135
	v_mov_b32_e32 v135, v2
	s_nop 1
	v_permlane32_swap_b32_e32 v2, v135
	s_and_saveexec_b64 s[0:1], s[38:39]
	v_add_f32_e32 v2, v2, v135
	ds_write_b32 v133, v2 offset:5632
	s_or_b64 exec, exec, s[0:1]
	v_add_u32_e32 v141, 0, v187
	v_add_u32_e32 v2, 0x21000, v141
	s_waitcnt lgkmcnt(0)
	s_barrier
	v_add_u32_e32 v212, 0x21000, v141
	ds_read_b128 v[218:221], v212
	ds_read_b128 v[222:225], v212 offset:512
	ds_read_b128 v[226:229], v212 offset:1024
	ds_read_b128 v[230:233], v212 offset:1536
	ds_read_b128 v[234:237], v212 offset:16
	ds_read_b128 v[238:241], v212 offset:528
	ds_read_b128 v[242:245], v212 offset:1040
	ds_read_b128 v[246:249], v212 offset:1552
	s_waitcnt lgkmcnt(7)
	v_mov_b64_e32 v[168:169], v[218:219]
	v_mov_b64_e32 v[170:171], v[220:221]
	ds_read_b128 v[218:221], v212 offset:4096
	v_add_u32_e32 v133, 0x21200, v141
	s_mov_b32 s0, 0x358637bd
	s_brev_b32 s1, 60
	v_mov_b32_e32 v194, v169
	v_mov_b32_e32 v195, v170
	v_mov_b32_e32 v169, v171
	v_pk_add_f32 v[168:169], v[194:195], v[168:169]
	s_nop 0
	v_add_f32_e32 v2, v168, v169
	s_waitcnt lgkmcnt(7)
	v_mov_b64_e32 v[168:169], v[222:223]
	v_mov_b64_e32 v[170:171], v[224:225]
	ds_read_b128 v[222:225], v212 offset:4608
	v_add_u32_e32 v133, 0x21400, v141
	v_mov_b32_e32 v194, v169
	v_mov_b32_e32 v195, v170
	v_mov_b32_e32 v169, v171
	v_pk_add_f32 v[168:169], v[194:195], v[168:169]
	s_nop 0
	v_add_f32_e32 v137, v168, v169
	s_waitcnt lgkmcnt(7)
	v_mov_b64_e32 v[168:169], v[226:227]
	v_mov_b64_e32 v[170:171], v[228:229]
	ds_read_b128 v[226:229], v212 offset:5120
	v_add_u32_e32 v133, 0x21600, v141
	v_mov_b32_e32 v194, v169
	v_mov_b32_e32 v195, v170
	v_mov_b32_e32 v169, v171
	v_pk_add_f32 v[168:169], v[194:195], v[168:169]
	s_nop 0
	v_add_f32_e32 v139, v168, v169
	s_waitcnt lgkmcnt(7)
	v_mov_b64_e32 v[168:169], v[230:231]
	v_mov_b64_e32 v[170:171], v[232:233]
	ds_read_b128 v[230:233], v212 offset:5632
	v_add_u32_e32 v133, 0x21010, v141
	v_mov_b32_e32 v194, v169
	v_mov_b32_e32 v195, v170
	v_mov_b32_e32 v169, v171
	v_pk_add_f32 v[168:169], v[194:195], v[168:169]
	s_nop 0
	v_add_f32_e32 v143, v168, v169
	s_waitcnt lgkmcnt(7)
; #define PG8_LAS __attribute__((address_space(3)))
;     __device__ __forceinline__ void operator()(const f32x4 (&acc)[2][2][4][2], const Unit& u, int wr, int wc, int fr, int fq) const {
;     ...
;                 for (int ai = 0; ai < 2; ++ai)
; #pragma unroll
;                     for (int bj = 0; bj < 2; ++bj)
; #pragma unroll
;                         for (int m = 0; m < 4; ++m) { const f32x4 r4 = *(const PG8_LAS f32x4*)(red + ((ai * HALF + wr * 64 + m * 16 + fr) * 2 + bj) * 4);
;                             sc[ai][bj][m] = __builtin_amdgcn_rsqf(((r4[0] + r4[1]) + (r4[2] + r4[3])) * (1.f / 128.f) + 1e-6f * var[ai][m]); }
	v_mov_b64_e32 v[168:169], v[234:235]
	v_mov_b64_e32 v[170:171], v[236:237]
	ds_read_b128 v[234:237], v212 offset:4112
	v_mov_b32_e32 v194, v169
	v_mov_b32_e32 v195, v170
	v_mov_b32_e32 v169, v171
	v_pk_add_f32 v[168:169], v[194:195], v[168:169]
	s_nop 0
	v_pk_add_f32 v[168:169], v[168:169], v[168:169] op_sel_hi:[0,1]
	v_mov_b32_e32 v133, v169
	v_pk_mul_f32 v[168:169], v[132:133], s[0:1]
	v_add_u32_e32 v133, 0x21210, v141
	v_fmamk_f32 v2, v2, 0x3c000000, v168
	v_rsq_f32_e32 v156, v2
	v_add_f32_e32 v2, v168, v169
	s_waitcnt lgkmcnt(7)
	v_mov_b64_e32 v[168:169], v[238:239]
	v_mov_b64_e32 v[170:171], v[240:241]
	ds_read_b128 v[238:241], v212 offset:4624
	v_rsq_f32_e32 v2, v2
	v_mov_b32_e32 v194, v169
	v_mov_b32_e32 v195, v170
	v_mov_b32_e32 v169, v171
	v_pk_add_f32 v[168:169], v[194:195], v[168:169]
	s_nop 0
	v_pk_add_f32 v[168:169], v[168:169], v[168:169] op_sel_hi:[0,1]
	v_mov_b32_e32 v135, v169
	v_pk_mul_f32 v[168:169], v[134:135], s[0:1]
	s_nop 0
	v_fmamk_f32 v133, v137, 0x3c000000, v168
	v_rsq_f32_e32 v180, v133
	v_add_f32_e32 v133, v168, v169
	v_rsq_f32_e32 v172, v133
	v_add_u32_e32 v133, 0x21410, v141
	s_waitcnt lgkmcnt(7)
	v_mov_b64_e32 v[168:169], v[242:243]
	v_mov_b64_e32 v[170:171], v[244:245]
	ds_read_b128 v[242:245], v212 offset:5136
	v_mov_b32_e32 v194, v169
	v_mov_b32_e32 v195, v170
	v_mov_b32_e32 v169, v171
	v_pk_add_f32 v[168:169], v[194:195], v[168:169]
	s_nop 0
	v_pk_add_f32 v[168:169], v[168:169], v[168:169] op_sel_hi:[0,1]
	v_mov_b32_e32 v137, v169
	v_pk_mul_f32 v[168:169], v[136:137], s[0:1]
	s_nop 0
	v_fmamk_f32 v133, v139, 0x3c000000, v168
	v_rsq_f32_e32 v158, v133
	v_add_f32_e32 v133, v168, v169
	v_rsq_f32_e32 v150, v133
	v_add_u32_e32 v133, 0x21610, v141
	s_waitcnt lgkmcnt(7)
	v_mov_b64_e32 v[168:169], v[246:247]
	v_mov_b64_e32 v[170:171], v[248:249]
	ds_read_b128 v[246:249], v212 offset:5648
	v_mov_b32_e32 v194, v169
	v_mov_b32_e32 v195, v170
	v_mov_b32_e32 v169, v171
	v_pk_add_f32 v[168:169], v[194:195], v[168:169]
	s_nop 0
	v_pk_add_f32 v[168:169], v[168:169], v[168:169] op_sel_hi:[0,1]
	v_mov_b32_e32 v139, v169
	v_pk_mul_f32 v[168:169], v[138:139], s[0:1]
	s_nop 0
	v_fmamk_f32 v133, v143, 0x3c000000, v168
	v_rsq_f32_e32 v182, v133
	v_add_f32_e32 v133, v168, v169
	v_rsq_f32_e32 v176, v133
	v_add_u32_e32 v133, 0x22000, v141
	s_waitcnt lgkmcnt(7)
	v_mov_b64_e32 v[168:169], v[218:219]
	v_mov_b64_e32 v[170:171], v[220:221]
	v_mov_b32_e32 v194, v169
	v_mov_b32_e32 v195, v170
	v_mov_b32_e32 v169, v171
	v_pk_add_f32 v[168:169], v[194:195], v[168:169]
	s_nop 0
	v_pk_add_f32 v[168:169], v[168:169], v[168:169] op_sel_hi:[0,1]
	v_mov_b32_e32 v143, v169
	v_pk_mul_f32 v[194:195], v[142:143], s[0:1]
	s_nop 0
	v_add_f32_e32 v133, v194, v195
	v_rsq_f32_e32 v154, v133
	v_add_u32_e32 v133, 0x22200, v141
	s_waitcnt lgkmcnt(6)
	v_mov_b64_e32 v[168:169], v[222:223]
	v_mov_b64_e32 v[170:171], v[224:225]
	v_mov_b32_e32 v196, v169
	v_mov_b32_e32 v197, v170
	v_mov_b32_e32 v169, v171
	v_pk_add_f32 v[168:169], v[196:197], v[168:169]
	s_nop 0
	v_pk_add_f32 v[168:169], v[168:169], v[168:169] op_sel_hi:[0,1]
	v_mov_b32_e32 v145, v169
	v_pk_mul_f32 v[196:197], v[144:145], s[0:1]
	s_nop 0
	v_add_f32_e32 v133, v196, v197
	v_rsq_f32_e32 v178, v133
	v_add_u32_e32 v133, 0x22400, v141
	s_waitcnt lgkmcnt(5)
	v_mov_b64_e32 v[168:169], v[226:227]
	v_mov_b64_e32 v[170:171], v[228:229]
	v_mov_b32_e32 v198, v169
	v_mov_b32_e32 v199, v170
	v_mov_b32_e32 v169, v171
	v_pk_add_f32 v[168:169], v[198:199], v[168:169]
	s_nop 0
	v_pk_add_f32 v[168:169], v[168:169], v[168:169] op_sel_hi:[0,1]
	v_mov_b32_e32 v147, v169
	v_pk_mul_f32 v[198:199], v[146:147], s[0:1]
	s_nop 0
	v_add_f32_e32 v133, v198, v199
	v_rsq_f32_e32 v152, v133
	v_add_u32_e32 v133, 0x22600, v141
	s_waitcnt lgkmcnt(4)
	v_mov_b64_e32 v[168:169], v[230:231]
	v_mov_b64_e32 v[170:171], v[232:233]
	v_mov_b32_e32 v208, v169
	v_mov_b32_e32 v209, v170
	v_mov_b32_e32 v169, v171
	v_pk_add_f32 v[168:169], v[208:209], v[168:169]
	s_nop 0
	v_pk_add_f32 v[168:169], v[168:169], v[168:169] op_sel_hi:[0,1]
	v_mov_b32_e32 v149, v169
	v_pk_mul_f32 v[208:209], v[148:149], s[0:1]
	s_nop 0
	v_add_f32_e32 v133, v208, v209
	v_rsq_f32_e32 v174, v133
	v_add_u32_e32 v133, 0x22010, v141
	s_waitcnt lgkmcnt(3)
	v_mov_b64_e32 v[168:169], v[234:235]
	v_mov_b64_e32 v[170:171], v[236:237]
	v_mov_b32_e32 v210, v169
	v_mov_b32_e32 v211, v170
	v_mov_b32_e32 v169, v171
	v_pk_add_f32 v[168:169], v[210:211], v[168:169]
	s_nop 0
	v_add_f32_e32 v133, v168, v169
	v_fmac_f32_e32 v194, 0x3c000000, v133
	v_add_u32_e32 v133, 0x22210, v141
	s_waitcnt lgkmcnt(2)
	v_mov_b64_e32 v[168:169], v[238:239]
	v_mov_b64_e32 v[170:171], v[240:241]
	v_rsq_f32_e32 v188, v194
	v_mov_b32_e32 v194, v169
	v_mov_b32_e32 v195, v170
	v_mov_b32_e32 v169, v171
	v_pk_add_f32 v[168:169], v[194:195], v[168:169]
	s_nop 0
	v_add_f32_e32 v133, v168, v169
	v_fmac_f32_e32 v196, 0x3c000000, v133
	v_add_u32_e32 v133, 0x22410, v141
	s_waitcnt lgkmcnt(1)
	v_mov_b64_e32 v[168:169], v[242:243]
	v_mov_b64_e32 v[170:171], v[244:245]
	v_rsq_f32_e32 v190, v196
	v_mov_b32_e32 v194, v169
	v_mov_b32_e32 v195, v170
	v_mov_b32_e32 v169, v171
	v_pk_add_f32 v[168:169], v[194:195], v[168:169]
	s_nop 0
	v_add_f32_e32 v133, v168, v169
	v_fmac_f32_e32 v198, 0x3c000000, v133
	v_add_u32_e32 v133, 0x22610, v141
	s_waitcnt lgkmcnt(0)
	v_mov_b64_e32 v[168:169], v[246:247]
	v_mov_b64_e32 v[170:171], v[248:249]
	v_rsq_f32_e32 v184, v198
	v_mov_b32_e32 v194, v169
	v_mov_b32_e32 v195, v170
	v_mov_b32_e32 v169, v171
	v_pk_add_f32 v[168:169], v[194:195], v[168:169]
	s_nop 0
	v_add_f32_e32 v133, v168, v169
	v_fmac_f32_e32 v208, 0x3c000000, v133
	v_rsq_f32_e32 v186, v208
	s_branch .LBB0_448
